# combined: MoE counted vmcnt waits + batched residual-epilogue loads in mixout/oproj + MoE per-tile gate/rowlist load batching
# baseline (speedup 1.0000x reference)
; __device__ __forceinline__ float bflo(uint32_t w) { return __uint_as_float(w << 16); }
; __device__ __forceinline__ float bfhi(uint32_t w) { return __uint_as_float(w & 0xffff0000u); }
; template <bool RES_BF16>
; __device__ __forceinline__ void gemm_residual(const u16* A, const u16* WT, const void* res_, float* pre, u16* smem) {
;     ...
;               [&](int j, int m, int nb, f32x4 (&a)[4]) {
;                 int mt = j % MT, nt = j / MT;
;                 const long off = (long)(mt * 128 + m) * DM + nt * 128 + nb;
; #pragma unroll
;                 for (int q = 0; q < 4; q++) {
;                   float4 xv;
;                   if (RES_BF16) {
;                     uint2 xw = *(const uint2*)((const u16*)res_ + off + q * 16);
;                     xv.x = bflo(xw.x); xv.y = bfhi(xw.x); xv.z = bflo(xw.y); xv.w = bfhi(xw.y);
;                   } else {
;                     xv = *(const float4*)((const float*)res_ + off + q * 16);
;                   }
;                   float4 r; r.x = DN_ALPHA * xv.x + a[q][0]; r.y = DN_ALPHA * xv.y + a[q][1]; r.z = DN_ALPHA * xv.z + a[q][2]; r.w = DN_ALPHA * xv.w + a[q][3];
;                   *(float4*)(pre + off + q * 16) = r;
;                 }
.LBB0_408:
	s_ashr_i32 s21, s2, 31
	s_lshr_b32 s21, s21, 26
	s_add_i32 s21, s2, s21
	s_and_b32 s24, s21, 0x1ffffc0
	s_sub_i32 s2, s2, s24
	v_lshl_add_u32 v96, s2, 7, v85
	s_lshl_b32 s2, s21, 1
	s_and_b32 s2, s2, 0xffffff80
	s_ashr_i32 s21, s2, 31
	v_ashrrev_i32_e32 v97, 31, v96
	v_mov_b32_e32 v99, s21
	v_or_b32_e32 v98, s2, v70
	v_lshlrev_b64 v[92:93], 11, v[96:97]
	v_lshl_add_u64 v[92:93], v[92:93], 0, v[98:99]
	v_lshlrev_b64 v[100:101], 2, v[92:93]
	v_lshl_add_u64 v[102:103], s[76:77], 0, v[100:101]
	global_load_dwordx4 v[92:95], v[102:103], off
	v_lshl_add_u64 v[100:101], s[14:15], 0, v[100:101]
	s_andn2_b64 vcc, exec, s[22:23]
	global_load_dwordx4 v[104:107], v[102:103], off offset:64
	global_load_dwordx4 v[108:111], v[102:103], off offset:128
	global_load_dwordx4 v[112:115], v[102:103], off offset:192
	v_lshl_add_u64 v[102:103], v[102:103], 0, s[4:5]
	global_load_dwordx4 v[116:119], v[102:103], off
	global_load_dwordx4 v[120:123], v[102:103], off offset:64
	global_load_dwordx4 v[124:127], v[102:103], off offset:128
	global_load_dwordx4 v[138:141], v[102:103], off offset:192
	v_lshl_add_u64 v[102:103], v[102:103], 0, s[4:5]
	global_load_dwordx4 v[142:145], v[102:103], off
	global_load_dwordx4 v[146:149], v[102:103], off offset:64
	global_load_dwordx4 v[150:153], v[102:103], off offset:128
	global_load_dwordx4 v[154:157], v[102:103], off offset:192
	v_lshl_add_u64 v[102:103], v[102:103], 0, s[4:5]
	global_load_dwordx4 v[158:161], v[102:103], off
	global_load_dwordx4 v[178:181], v[102:103], off offset:64
	global_load_dwordx4 v[96:99], v[102:103], off offset:128
	s_waitcnt vmcnt(14)
	v_pk_fma_f32 v[60:61], v[92:93], s[20:21], v[60:61] op_sel_hi:[1,0,1]
	v_pk_fma_f32 v[62:63], v[94:95], s[20:21], v[62:63] op_sel_hi:[1,0,1]
	global_store_dwordx4 v[100:101], v[60:63], off
	global_load_dwordx4 v[60:63], v[102:103], off offset:192
	s_waitcnt vmcnt(15)
	v_pk_fma_f32 v[56:57], v[104:105], s[20:21], v[56:57] op_sel_hi:[1,0,1]
	v_pk_fma_f32 v[58:59], v[106:107], s[20:21], v[58:59] op_sel_hi:[1,0,1]
	global_store_dwordx4 v[100:101], v[56:59], off offset:64
	s_waitcnt vmcnt(15)
	v_pk_fma_f32 v[52:53], v[108:109], s[20:21], v[52:53] op_sel_hi:[1,0,1]
	v_pk_fma_f32 v[54:55], v[110:111], s[20:21], v[54:55] op_sel_hi:[1,0,1]
	global_store_dwordx4 v[100:101], v[52:55], off offset:128
	s_waitcnt vmcnt(15)
	v_pk_fma_f32 v[48:49], v[112:113], s[20:21], v[48:49] op_sel_hi:[1,0,1]
	v_pk_fma_f32 v[50:51], v[114:115], s[20:21], v[50:51] op_sel_hi:[1,0,1]
	global_store_dwordx4 v[100:101], v[48:51], off offset:192
	v_lshl_add_u64 v[100:101], v[100:101], 0, s[4:5]
	s_waitcnt vmcnt(15)
	v_pk_fma_f32 v[44:45], v[116:117], s[20:21], v[44:45] op_sel_hi:[1,0,1]
	v_pk_fma_f32 v[46:47], v[118:119], s[20:21], v[46:47] op_sel_hi:[1,0,1]
	global_store_dwordx4 v[100:101], v[44:47], off
	s_waitcnt vmcnt(15)
	v_pk_fma_f32 v[40:41], v[120:121], s[20:21], v[40:41] op_sel_hi:[1,0,1]
	v_pk_fma_f32 v[42:43], v[122:123], s[20:21], v[42:43] op_sel_hi:[1,0,1]
	global_store_dwordx4 v[100:101], v[40:43], off offset:64
	s_waitcnt vmcnt(15)
	v_pk_fma_f32 v[36:37], v[124:125], s[20:21], v[36:37] op_sel_hi:[1,0,1]
	v_pk_fma_f32 v[38:39], v[126:127], s[20:21], v[38:39] op_sel_hi:[1,0,1]
	global_store_dwordx4 v[100:101], v[36:39], off offset:128
	s_waitcnt vmcnt(15)
	v_pk_fma_f32 v[32:33], v[138:139], s[20:21], v[32:33] op_sel_hi:[1,0,1]
	v_pk_fma_f32 v[34:35], v[140:141], s[20:21], v[34:35] op_sel_hi:[1,0,1]
	global_store_dwordx4 v[100:101], v[32:35], off offset:192
	v_lshl_add_u64 v[100:101], v[100:101], 0, s[4:5]
	s_waitcnt vmcnt(15)
	v_pk_fma_f32 v[28:29], v[142:143], s[20:21], v[28:29] op_sel_hi:[1,0,1]
	v_pk_fma_f32 v[30:31], v[144:145], s[20:21], v[30:31] op_sel_hi:[1,0,1]
	global_store_dwordx4 v[100:101], v[28:31], off
	s_waitcnt vmcnt(15)
	v_pk_fma_f32 v[24:25], v[146:147], s[20:21], v[24:25] op_sel_hi:[1,0,1]
	v_pk_fma_f32 v[26:27], v[148:149], s[20:21], v[26:27] op_sel_hi:[1,0,1]
	global_store_dwordx4 v[100:101], v[24:27], off offset:64
	s_waitcnt vmcnt(15)
	v_pk_fma_f32 v[20:21], v[150:151], s[20:21], v[20:21] op_sel_hi:[1,0,1]
	v_pk_fma_f32 v[22:23], v[152:153], s[20:21], v[22:23] op_sel_hi:[1,0,1]
	global_store_dwordx4 v[100:101], v[20:23], off offset:128
	s_waitcnt vmcnt(15)
	v_pk_fma_f32 v[16:17], v[154:155], s[20:21], v[16:17] op_sel_hi:[1,0,1]
	v_pk_fma_f32 v[18:19], v[156:157], s[20:21], v[18:19] op_sel_hi:[1,0,1]
	global_store_dwordx4 v[100:101], v[16:19], off offset:192
	v_lshl_add_u64 v[100:101], v[100:101], 0, s[4:5]
	s_waitcnt vmcnt(15)
	v_pk_fma_f32 v[12:13], v[158:159], s[20:21], v[12:13] op_sel_hi:[1,0,1]
	v_pk_fma_f32 v[14:15], v[160:161], s[20:21], v[14:15] op_sel_hi:[1,0,1]
	global_store_dwordx4 v[100:101], v[12:15], off
	s_waitcnt vmcnt(15)
	v_pk_fma_f32 v[8:9], v[178:179], s[20:21], v[8:9] op_sel_hi:[1,0,1]
	v_pk_fma_f32 v[10:11], v[180:181], s[20:21], v[10:11] op_sel_hi:[1,0,1]
	global_store_dwordx4 v[100:101], v[8:11], off offset:64
	s_waitcnt vmcnt(15)
	v_pk_fma_f32 v[4:5], v[96:97], s[20:21], v[4:5] op_sel_hi:[1,0,1]
	v_pk_fma_f32 v[6:7], v[98:99], s[20:21], v[6:7] op_sel_hi:[1,0,1]
	global_store_dwordx4 v[100:101], v[4:7], off offset:128
	s_waitcnt vmcnt(14)
	v_pk_fma_f32 v[0:1], v[60:61], s[20:21], v[0:1] op_sel_hi:[1,0,1]
	v_pk_fma_f32 v[2:3], v[62:63], s[20:21], v[2:3] op_sel_hi:[1,0,1]
	global_store_dwordx4 v[100:101], v[0:3], off offset:192
	s_cbranch_vccz .LBB0_413

; __device__ __forceinline__ float bflo(uint32_t w) { return __uint_as_float(w << 16); }
; __device__ __forceinline__ float bfhi(uint32_t w) { return __uint_as_float(w & 0xffff0000u); }
; template <bool RES_BF16>
; __device__ __forceinline__ void gemm_residual(const u16* A, const u16* WT, const void* res_, float* pre, u16* smem) {
;     ...
;               [&](int j, int m, int nb, f32x4 (&a)[4]) {
;                 int mt = j % MT, nt = j / MT;
;                 const long off = (long)(mt * 128 + m) * DM + nt * 128 + nb;
; #pragma unroll
;                 for (int q = 0; q < 4; q++) {
;                   float4 xv;
;                   if (RES_BF16) {
;                     uint2 xw = *(const uint2*)((const u16*)res_ + off + q * 16);
;                     xv.x = bflo(xw.x); xv.y = bfhi(xw.x); xv.z = bflo(xw.y); xv.w = bfhi(xw.y);
;                   } else {
;                     xv = *(const float4*)((const float*)res_ + off + q * 16);
;                   }
;                   float4 r; r.x = DN_ALPHA * xv.x + a[q][0]; r.y = DN_ALPHA * xv.y + a[q][1]; r.z = DN_ALPHA * xv.z + a[q][2]; r.w = DN_ALPHA * xv.w + a[q][3];
;                   *(float4*)(pre + off + q * 16) = r;
;                 }
.LBB0_758:
	s_ashr_i32 s21, s2, 31
	s_lshr_b32 s21, s21, 26
	s_add_i32 s21, s2, s21
	s_and_b32 s24, s21, 0x1ffffc0
	s_sub_i32 s2, s2, s24
	v_lshl_add_u32 v78, s2, 7, v89
	s_lshl_b32 s2, s21, 1
	s_and_b32 s2, s2, 0xffffff80
	s_ashr_i32 s21, s2, 31
	v_ashrrev_i32_e32 v79, 31, v78
	v_mov_b32_e32 v77, s21
	v_or_b32_e32 v76, s2, v70
	v_lshlrev_b64 v[96:97], 11, v[78:79]
	v_lshl_add_u64 v[96:97], v[96:97], 0, v[76:77]
	v_lshl_add_u64 v[98:99], v[96:97], 1, s[28:29]
	v_lshl_add_u64 v[96:97], v[96:97], 2, s[14:15]
	s_mov_b64 s[24:25], 0x10000
	global_load_dwordx2 v[100:101], v[98:99], off
	global_load_dwordx2 v[102:103], v[98:99], off offset:32
	global_load_dwordx2 v[104:105], v[98:99], off offset:64
	global_load_dwordx2 v[106:107], v[98:99], off offset:96
	v_lshl_add_u64 v[98:99], v[98:99], 0, s[24:25]
	global_load_dwordx2 v[108:109], v[98:99], off
	global_load_dwordx2 v[110:111], v[98:99], off offset:32
	global_load_dwordx2 v[112:113], v[98:99], off offset:64
	global_load_dwordx2 v[114:115], v[98:99], off offset:96
	v_lshl_add_u64 v[98:99], v[98:99], 0, s[24:25]
	global_load_dwordx2 v[116:117], v[98:99], off
	global_load_dwordx2 v[118:119], v[98:99], off offset:32
	global_load_dwordx2 v[120:121], v[98:99], off offset:64
	global_load_dwordx2 v[122:123], v[98:99], off offset:96
	v_lshl_add_u64 v[98:99], v[98:99], 0, s[24:25]
	global_load_dwordx2 v[124:125], v[98:99], off
	global_load_dwordx2 v[126:127], v[98:99], off offset:32
	global_load_dwordx2 v[134:135], v[98:99], off offset:64
	global_load_dwordx2 v[136:137], v[98:99], off offset:96
	s_andn2_b64 vcc, exec, s[22:23]
	s_waitcnt vmcnt(15)
	v_lshlrev_b32_e32 v138, 16, v100
	v_and_b32_e32 v139, 0xffff0000, v100
	v_lshlrev_b32_e32 v140, 16, v101
	v_and_b32_e32 v141, 0xffff0000, v101
	v_pk_fma_f32 v[60:61], v[138:139], s[20:21], v[60:61] op_sel_hi:[1,0,1]
	v_pk_fma_f32 v[62:63], v[140:141], s[20:21], v[62:63] op_sel_hi:[1,0,1]
	global_store_dwordx4 v[96:97], v[60:63], off
	s_waitcnt vmcnt(15)
	v_lshlrev_b32_e32 v138, 16, v102
	v_and_b32_e32 v139, 0xffff0000, v102
	v_lshlrev_b32_e32 v140, 16, v103
	v_and_b32_e32 v141, 0xffff0000, v103
	v_pk_fma_f32 v[56:57], v[138:139], s[20:21], v[56:57] op_sel_hi:[1,0,1]
	v_pk_fma_f32 v[58:59], v[140:141], s[20:21], v[58:59] op_sel_hi:[1,0,1]
	global_store_dwordx4 v[96:97], v[56:59], off offset:64
	s_waitcnt vmcnt(15)
	v_lshlrev_b32_e32 v138, 16, v104
	v_and_b32_e32 v139, 0xffff0000, v104
	v_lshlrev_b32_e32 v140, 16, v105
	v_and_b32_e32 v141, 0xffff0000, v105
	v_pk_fma_f32 v[52:53], v[138:139], s[20:21], v[52:53] op_sel_hi:[1,0,1]
	v_pk_fma_f32 v[54:55], v[140:141], s[20:21], v[54:55] op_sel_hi:[1,0,1]
	global_store_dwordx4 v[96:97], v[52:55], off offset:128
	s_waitcnt vmcnt(15)
	v_lshlrev_b32_e32 v138, 16, v106
	v_and_b32_e32 v139, 0xffff0000, v106
	v_lshlrev_b32_e32 v140, 16, v107
	v_and_b32_e32 v141, 0xffff0000, v107
	v_pk_fma_f32 v[48:49], v[138:139], s[20:21], v[48:49] op_sel_hi:[1,0,1]
	v_pk_fma_f32 v[50:51], v[140:141], s[20:21], v[50:51] op_sel_hi:[1,0,1]
	global_store_dwordx4 v[96:97], v[48:51], off offset:192
	v_lshl_add_u64 v[96:97], v[96:97], 0, s[6:7]
	s_waitcnt vmcnt(15)
	v_lshlrev_b32_e32 v138, 16, v108
	v_and_b32_e32 v139, 0xffff0000, v108
	v_lshlrev_b32_e32 v140, 16, v109
	v_and_b32_e32 v141, 0xffff0000, v109
	v_pk_fma_f32 v[44:45], v[138:139], s[20:21], v[44:45] op_sel_hi:[1,0,1]
	v_pk_fma_f32 v[46:47], v[140:141], s[20:21], v[46:47] op_sel_hi:[1,0,1]
	global_store_dwordx4 v[96:97], v[44:47], off
	s_waitcnt vmcnt(15)
	v_lshlrev_b32_e32 v138, 16, v110
	v_and_b32_e32 v139, 0xffff0000, v110
	v_lshlrev_b32_e32 v140, 16, v111
	v_and_b32_e32 v141, 0xffff0000, v111
	v_pk_fma_f32 v[40:41], v[138:139], s[20:21], v[40:41] op_sel_hi:[1,0,1]
	v_pk_fma_f32 v[42:43], v[140:141], s[20:21], v[42:43] op_sel_hi:[1,0,1]
	global_store_dwordx4 v[96:97], v[40:43], off offset:64
	s_waitcnt vmcnt(15)
; __device__ __forceinline__ float bflo(uint32_t w) { return __uint_as_float(w << 16); }
; __device__ __forceinline__ float bfhi(uint32_t w) { return __uint_as_float(w & 0xffff0000u); }
; template <bool RES_BF16>
; __device__ __forceinline__ void gemm_residual(const u16* A, const u16* WT, const void* res_, float* pre, u16* smem) {
;     ...
;               [&](int j, int m, int nb, f32x4 (&a)[4]) {
;                 int mt = j % MT, nt = j / MT;
;                 const long off = (long)(mt * 128 + m) * DM + nt * 128 + nb;
; #pragma unroll
;                 for (int q = 0; q < 4; q++) {
;                   float4 xv;
;                   if (RES_BF16) {
;                     uint2 xw = *(const uint2*)((const u16*)res_ + off + q * 16);
;                     xv.x = bflo(xw.x); xv.y = bfhi(xw.x); xv.z = bflo(xw.y); xv.w = bfhi(xw.y);
;                   } else {
;                     xv = *(const float4*)((const float*)res_ + off + q * 16);
;                   }
;                   float4 r; r.x = DN_ALPHA * xv.x + a[q][0]; r.y = DN_ALPHA * xv.y + a[q][1]; r.z = DN_ALPHA * xv.z + a[q][2]; r.w = DN_ALPHA * xv.w + a[q][3];
;                   *(float4*)(pre + off + q * 16) = r;
;                 }
	v_lshlrev_b32_e32 v138, 16, v112
	v_and_b32_e32 v139, 0xffff0000, v112
	v_lshlrev_b32_e32 v140, 16, v113
	v_and_b32_e32 v141, 0xffff0000, v113
	v_pk_fma_f32 v[36:37], v[138:139], s[20:21], v[36:37] op_sel_hi:[1,0,1]
	v_pk_fma_f32 v[38:39], v[140:141], s[20:21], v[38:39] op_sel_hi:[1,0,1]
	global_store_dwordx4 v[96:97], v[36:39], off offset:128
	s_waitcnt vmcnt(15)
	v_lshlrev_b32_e32 v138, 16, v114
	v_and_b32_e32 v139, 0xffff0000, v114
	v_lshlrev_b32_e32 v140, 16, v115
	v_and_b32_e32 v141, 0xffff0000, v115
	v_pk_fma_f32 v[32:33], v[138:139], s[20:21], v[32:33] op_sel_hi:[1,0,1]
	v_pk_fma_f32 v[34:35], v[140:141], s[20:21], v[34:35] op_sel_hi:[1,0,1]
	global_store_dwordx4 v[96:97], v[32:35], off offset:192
	v_lshl_add_u64 v[96:97], v[96:97], 0, s[6:7]
	s_waitcnt vmcnt(15)
	v_lshlrev_b32_e32 v138, 16, v116
	v_and_b32_e32 v139, 0xffff0000, v116
	v_lshlrev_b32_e32 v140, 16, v117
	v_and_b32_e32 v141, 0xffff0000, v117
	v_pk_fma_f32 v[28:29], v[138:139], s[20:21], v[28:29] op_sel_hi:[1,0,1]
	v_pk_fma_f32 v[30:31], v[140:141], s[20:21], v[30:31] op_sel_hi:[1,0,1]
	global_store_dwordx4 v[96:97], v[28:31], off
	s_waitcnt vmcnt(15)
	v_lshlrev_b32_e32 v138, 16, v118
	v_and_b32_e32 v139, 0xffff0000, v118
	v_lshlrev_b32_e32 v140, 16, v119
	v_and_b32_e32 v141, 0xffff0000, v119
	v_pk_fma_f32 v[24:25], v[138:139], s[20:21], v[24:25] op_sel_hi:[1,0,1]
	v_pk_fma_f32 v[26:27], v[140:141], s[20:21], v[26:27] op_sel_hi:[1,0,1]
	global_store_dwordx4 v[96:97], v[24:27], off offset:64
	s_waitcnt vmcnt(15)
	v_lshlrev_b32_e32 v138, 16, v120
	v_and_b32_e32 v139, 0xffff0000, v120
	v_lshlrev_b32_e32 v140, 16, v121
	v_and_b32_e32 v141, 0xffff0000, v121
	v_pk_fma_f32 v[20:21], v[138:139], s[20:21], v[20:21] op_sel_hi:[1,0,1]
	v_pk_fma_f32 v[22:23], v[140:141], s[20:21], v[22:23] op_sel_hi:[1,0,1]
	global_store_dwordx4 v[96:97], v[20:23], off offset:128
	s_waitcnt vmcnt(15)
	v_lshlrev_b32_e32 v138, 16, v122
	v_and_b32_e32 v139, 0xffff0000, v122
	v_lshlrev_b32_e32 v140, 16, v123
	v_and_b32_e32 v141, 0xffff0000, v123
	v_pk_fma_f32 v[16:17], v[138:139], s[20:21], v[16:17] op_sel_hi:[1,0,1]
	v_pk_fma_f32 v[18:19], v[140:141], s[20:21], v[18:19] op_sel_hi:[1,0,1]
	global_store_dwordx4 v[96:97], v[16:19], off offset:192
	v_lshl_add_u64 v[96:97], v[96:97], 0, s[6:7]
	s_waitcnt vmcnt(15)
	v_lshlrev_b32_e32 v138, 16, v124
	v_and_b32_e32 v139, 0xffff0000, v124
	v_lshlrev_b32_e32 v140, 16, v125
	v_and_b32_e32 v141, 0xffff0000, v125
	v_pk_fma_f32 v[12:13], v[138:139], s[20:21], v[12:13] op_sel_hi:[1,0,1]
	v_pk_fma_f32 v[14:15], v[140:141], s[20:21], v[14:15] op_sel_hi:[1,0,1]
	global_store_dwordx4 v[96:97], v[12:15], off
	s_waitcnt vmcnt(15)
	v_lshlrev_b32_e32 v138, 16, v126
	v_and_b32_e32 v139, 0xffff0000, v126
	v_lshlrev_b32_e32 v140, 16, v127
	v_and_b32_e32 v141, 0xffff0000, v127
	v_pk_fma_f32 v[8:9], v[138:139], s[20:21], v[8:9] op_sel_hi:[1,0,1]
	v_pk_fma_f32 v[10:11], v[140:141], s[20:21], v[10:11] op_sel_hi:[1,0,1]
	global_store_dwordx4 v[96:97], v[8:11], off offset:64
	s_waitcnt vmcnt(15)
	v_lshlrev_b32_e32 v138, 16, v134
	v_and_b32_e32 v139, 0xffff0000, v134
	v_lshlrev_b32_e32 v140, 16, v135
	v_and_b32_e32 v141, 0xffff0000, v135
	v_pk_fma_f32 v[4:5], v[138:139], s[20:21], v[4:5] op_sel_hi:[1,0,1]
	v_pk_fma_f32 v[6:7], v[140:141], s[20:21], v[6:7] op_sel_hi:[1,0,1]
	global_store_dwordx4 v[96:97], v[4:7], off offset:128
	s_waitcnt vmcnt(15)
	v_lshlrev_b32_e32 v138, 16, v136
	v_and_b32_e32 v139, 0xffff0000, v136
	v_lshlrev_b32_e32 v140, 16, v137
	v_and_b32_e32 v141, 0xffff0000, v137
	v_pk_fma_f32 v[0:1], v[138:139], s[20:21], v[0:1] op_sel_hi:[1,0,1]
	v_pk_fma_f32 v[2:3], v[140:141], s[20:21], v[2:3] op_sel_hi:[1,0,1]
	global_store_dwordx4 v[96:97], v[0:3], off offset:192
	s_cbranch_vccz .LBB0_763

; #define LOAD_W(R, k0)                                                           \
;   {                                                                             \
;     _Pragma("unroll") for (int i = 0; i < 8; i++) R[i] = *(const f32x4*)(wp0 + (long)((k0) + 8 * i) * kstride); \
;   }
; template <class WM, class Epi>
; __device__ __forceinline__ void gemm_tile_wf32(const u16* __restrict__ A, long lda, const int* arow, WM wmap, long kstride, int K,
;                                                u16* smem, Epi epi) {
;     ...
;     asm volatile("s_waitcnt vmcnt(8)" ::: "memory");
;     __syncthreads();
;     STAGE_A((kt + 1) << 6, 1);
;     if (kt + 2 < nk) LOAD_W(wr0, (kt + 2) << 6);
;     COMPUTE(0);
;     WRITE_W(wr1, 1);
;     if (kt + 2 < nk) { asm volatile("s_waitcnt vmcnt(8)" ::: "memory"); } else { asm volatile("s_waitcnt vmcnt(0)" ::: "memory"); }
;     __syncthreads();
;     if (kt + 2 < nk) { STAGE_A((kt + 2) << 6, 0); }
;     if (kt + 3 < nk) LOAD_W(wr1, (kt + 3) << 6);
;     COMPUTE(1);
;     if (kt + 2 < nk) WRITE_W(wr0, 0);
.LBB0_892:
	s_waitcnt vmcnt(8)
	v_cvt_pk_bf16_f32 v156, v32, v33
	v_cvt_pk_bf16_f32 v157, v34, v35
	ds_write_b64 v188, v[156:157] offset:16384
	v_cvt_pk_bf16_f32 v156, v36, v37
	v_cvt_pk_bf16_f32 v157, v38, v39
	ds_write_b64 v189, v[156:157] offset:16384
	v_cvt_pk_bf16_f32 v156, v48, v49
	v_cvt_pk_bf16_f32 v157, v50, v51
	ds_write_b64 v188, v[156:157] offset:20480
	v_cvt_pk_bf16_f32 v156, v52, v53
	v_cvt_pk_bf16_f32 v157, v54, v55
	ds_write_b64 v189, v[156:157] offset:20480
	v_cvt_pk_bf16_f32 v156, v64, v65
	v_cvt_pk_bf16_f32 v157, v66, v67
	ds_write_b64 v188, v[156:157] offset:24576
	v_cvt_pk_bf16_f32 v156, v68, v69
	v_cvt_pk_bf16_f32 v157, v70, v71
	ds_write_b64 v189, v[156:157] offset:24576
	v_cvt_pk_bf16_f32 v156, v80, v81
	v_cvt_pk_bf16_f32 v157, v82, v83
	ds_write_b64 v188, v[156:157] offset:28672
	v_cvt_pk_bf16_f32 v156, v84, v85
	v_cvt_pk_bf16_f32 v157, v86, v87
	v_add_u32_e32 v160, 0x8000, v186
	ds_write_b64 v189, v[156:157] offset:28672
	v_lshl_add_u64 v[156:157], s[30:31], 0, v[146:147]
	v_readfirstlane_b32 s34, v160
	v_lshl_add_u64 v[158:159], v[156:157], 0, s[22:23]
	s_mov_b32 m0, s34
	v_add_u32_e32 v162, 0x9000, v186
	s_waitcnt vmcnt(8)
	s_waitcnt lgkmcnt(0)
	s_barrier
	global_load_lds_dwordx4 v[158:159], off
	v_lshl_add_u64 v[158:159], s[30:31], 0, v[148:149]
	v_readfirstlane_b32 s34, v162
	v_lshl_add_u64 v[160:161], v[158:159], 0, s[22:23]
	s_mov_b32 m0, s34
	v_add_u32_e32 v170, 0xa000, v186
	global_load_lds_dwordx4 v[160:161], off
	v_lshl_add_u64 v[160:161], s[30:31], 0, v[150:151]
	v_readfirstlane_b32 s34, v170
	v_lshl_add_u64 v[162:163], v[160:161], 0, s[22:23]
	s_mov_b32 m0, s34
	v_add_u32_e32 v172, 0xb000, v186
	global_load_lds_dwordx4 v[162:163], off
	v_lshl_add_u64 v[162:163], s[30:31], 0, v[152:153]
	v_readfirstlane_b32 s34, v172
	v_lshl_add_u64 v[170:171], v[162:163], 0, s[22:23]
	s_mov_b32 m0, s34
	s_cmp_lt_u32 s21, 30
	global_load_lds_dwordx4 v[170:171], off
	s_cselect_b64 s[36:37], -1, 0
	s_cmp_gt_u32 s21, 29
	s_cselect_b64 s[34:35], -1, 0
	s_and_b64 vcc, exec, s[34:35]
	s_cbranch_vccnz .LBB0_894
	v_add_co_u32_e32 v32, vcc, 0xfffc4000, v154
	s_nop 1
	v_addc_co_u32_e32 v33, vcc, -1, v155, vcc
	v_add_co_u32_e32 v36, vcc, 0xfffc8000, v154
	s_nop 1
	v_addc_co_u32_e32 v37, vcc, -1, v155, vcc
	v_add_co_u32_e32 v48, vcc, 0xfffcc000, v154
	global_load_dwordx4 v[32:35], v[32:33], off
	s_nop 0
	global_load_dwordx4 v[36:39], v[36:37], off
	v_addc_co_u32_e32 v49, vcc, -1, v155, vcc
	v_add_co_u32_e32 v52, vcc, 0xfffd0000, v154
	s_nop 1
	v_addc_co_u32_e32 v53, vcc, -1, v155, vcc
	v_add_co_u32_e32 v64, vcc, 0xfffd4000, v154
	global_load_dwordx4 v[48:51], v[48:49], off
	s_nop 0
	global_load_dwordx4 v[52:55], v[52:53], off
	v_addc_co_u32_e32 v65, vcc, -1, v155, vcc
	v_add_co_u32_e32 v68, vcc, 0xfffd8000, v154
	s_nop 1
	v_addc_co_u32_e32 v69, vcc, -1, v155, vcc
	v_add_co_u32_e32 v80, vcc, 0xfffdc000, v154
	global_load_dwordx4 v[64:67], v[64:65], off
	s_nop 0
	global_load_dwordx4 v[68:71], v[68:69], off
	v_addc_co_u32_e32 v81, vcc, -1, v155, vcc
	v_add_co_u32_e32 v84, vcc, 0xfffe0000, v154
	s_nop 1
	v_addc_co_u32_e32 v85, vcc, -1, v155, vcc
	global_load_dwordx4 v[80:83], v[80:81], off
	s_nop 0
	global_load_dwordx4 v[84:87], v[84:85], off
; template <class WM, class Epi>
; __device__ __forceinline__ void gemm_tile_wf32(const u16* __restrict__ A, long lda, const int* arow, WM wmap, long kstride, int K,
;                                                u16* smem, Epi epi) {
;     ...
;     COMPUTE(0);
;     WRITE_W(wr1, 1);
.LBB0_894:
	ds_read_b64_tr_b16 v[204:205], v191 offset:16384
	ds_read_b64_tr_b16 v[206:207], v192 offset:17408
	ds_read_b128 v[208:211], v190
	ds_read_b128 v[212:215], v190 offset:2048
	ds_read_b64_tr_b16 v[218:219], v192 offset:25600
	ds_read_b64_tr_b16 v[216:217], v191 offset:24576
	ds_read_b64_tr_b16 v[220:221], v193 offset:16384
	ds_read_b64_tr_b16 v[222:223], v194 offset:17408
	ds_read_b64_tr_b16 v[226:227], v194 offset:25600
	ds_read_b64_tr_b16 v[224:225], v193 offset:24576
	ds_read_b64_tr_b16 v[228:229], v195 offset:16384
	ds_read_b64_tr_b16 v[230:231], v196 offset:17408
	ds_read_b64_tr_b16 v[234:235], v196 offset:25600
	ds_read_b64_tr_b16 v[232:233], v195 offset:24576
	ds_read_b64_tr_b16 v[236:237], v197 offset:16384
	ds_read_b64_tr_b16 v[238:239], v198 offset:17408
	ds_read_b64_tr_b16 v[242:243], v198 offset:25600
	ds_read_b64_tr_b16 v[240:241], v197 offset:24576
	s_waitcnt lgkmcnt(0)
	v_mfma_f32_16x16x32_bf16 v[124:127], v[204:207], v[208:211], v[124:127]
	s_mov_b64 s[38:39], -1
	s_and_b64 vcc, exec, s[34:35]
	v_mfma_f32_16x16x32_bf16 v[120:123], v[220:223], v[208:211], v[120:123]
	v_mfma_f32_16x16x32_bf16 v[116:119], v[228:231], v[208:211], v[116:119]
	v_mfma_f32_16x16x32_bf16 v[112:115], v[236:239], v[208:211], v[112:115]
	v_mfma_f32_16x16x32_bf16 v[108:111], v[204:207], v[212:215], v[108:111]
	v_mfma_f32_16x16x32_bf16 v[208:211], v[220:223], v[212:215], v[104:107]
	v_mfma_f32_16x16x32_bf16 v[44:47], v[228:231], v[212:215], v[44:47]
	v_mfma_f32_16x16x32_bf16 v[40:43], v[236:239], v[212:215], v[40:43]
	s_nop 0
	ds_read_b128 v[104:107], v190 offset:4096
	ds_read_b128 v[212:215], v190 offset:6144
	s_waitcnt lgkmcnt(0)
	v_mfma_f32_16x16x32_bf16 v[244:247], v[204:207], v[104:107], v[28:31]
	v_mfma_f32_16x16x32_bf16 v[248:251], v[220:223], v[104:107], v[24:27]
	v_mfma_f32_16x16x32_bf16 v[170:173], v[228:231], v[104:107], v[20:23]
	s_cbranch_vccnz .Lmoe0_w4
	s_waitcnt vmcnt(12)
.Lmoe0_wd:
	s_nop 1
	v_cvt_pk_bf16_f32 v24, v56, v57
	v_cvt_pk_bf16_f32 v25, v58, v59
	v_mfma_f32_16x16x32_bf16 v[204:207], v[204:207], v[212:215], v[12:15]
	v_mfma_f32_16x16x32_bf16 v[220:223], v[220:223], v[212:215], v[8:11]
	v_mfma_f32_16x16x32_bf16 v[228:231], v[228:231], v[212:215], v[4:7]
	v_mfma_f32_16x16x32_bf16 v[212:215], v[236:239], v[212:215], v[0:3]
	s_nop 2
	ds_read_b128 v[0:3], v199
	ds_read_b128 v[20:23], v199 offset:2048
	v_mfma_f32_16x16x32_bf16 v[174:177], v[236:239], v[104:107], v[16:19]
	s_waitcnt lgkmcnt(0)
	v_mfma_f32_16x16x32_bf16 v[104:107], v[216:219], v[0:3], v[124:127]
	v_mfma_f32_16x16x32_bf16 v[4:7], v[216:219], v[20:23], v[108:111]
	s_nop 2
	ds_read_b128 v[108:111], v199 offset:4096
	ds_read_b128 v[124:127], v199 offset:6144
	ds_write_b64 v188, v[24:25] offset:49152
	v_mfma_f32_16x16x32_bf16 v[28:31], v[224:227], v[0:3], v[120:123]
	v_mfma_f32_16x16x32_bf16 v[16:19], v[232:235], v[0:3], v[116:119]
	s_nop 1
	v_cvt_pk_bf16_f32 v120, v96, v97
	v_cvt_pk_bf16_f32 v121, v98, v99
	v_mfma_f32_16x16x32_bf16 v[0:3], v[240:243], v[0:3], v[112:115]
	v_cvt_pk_bf16_f32 v116, v92, v93
	v_cvt_pk_bf16_f32 v117, v94, v95
	v_mfma_f32_16x16x32_bf16 v[8:11], v[224:227], v[20:23], v[208:211]
	v_cvt_pk_bf16_f32 v112, v76, v77
	v_cvt_pk_bf16_f32 v113, v78, v79
	v_mfma_f32_16x16x32_bf16 v[12:15], v[232:235], v[20:23], v[44:47]
	v_mfma_f32_16x16x32_bf16 v[20:23], v[240:243], v[20:23], v[40:43]
	s_nop 1
	v_cvt_pk_bf16_f32 v44, v72, v73
	v_cvt_pk_bf16_f32 v45, v74, v75
	v_cvt_pk_bf16_f32 v40, v60, v61
	v_cvt_pk_bf16_f32 v41, v62, v63
	ds_write_b64 v189, v[40:41] offset:49152
	ds_write_b64 v188, v[44:45] offset:53248
	ds_write_b64 v189, v[112:113] offset:53248
	v_cvt_pk_bf16_f32 v112, v88, v89
	v_cvt_pk_bf16_f32 v113, v90, v91
	s_waitcnt lgkmcnt(0)
	v_mfma_f32_16x16x32_bf16 v[24:27], v[216:219], v[108:111], v[244:247]
	ds_write_b64 v188, v[112:113] offset:57344
	ds_write_b64 v189, v[116:117] offset:57344
	ds_write_b64 v188, v[120:121] offset:61440
	v_mfma_f32_16x16x32_bf16 v[40:43], v[224:227], v[108:111], v[248:251]
	v_mfma_f32_16x16x32_bf16 v[44:47], v[232:235], v[108:111], v[170:173]
	v_mfma_f32_16x16x32_bf16 v[108:111], v[240:243], v[108:111], v[174:177]
	s_nop 1
	v_cvt_pk_bf16_f32 v170, v100, v101
	v_cvt_pk_bf16_f32 v171, v102, v103
	ds_write_b64 v189, v[170:171] offset:61440
	v_mfma_f32_16x16x32_bf16 v[112:115], v[216:219], v[124:127], v[204:207]
	v_mfma_f32_16x16x32_bf16 v[116:119], v[224:227], v[124:127], v[220:223]
	v_mfma_f32_16x16x32_bf16 v[120:123], v[232:235], v[124:127], v[228:231]
	v_mfma_f32_16x16x32_bf16 v[124:127], v[240:243], v[124:127], v[212:215]
	s_cbranch_vccz .LBB0_896
	s_waitcnt vmcnt(0)
	s_mov_b64 s[38:39], 0

; template <class WM, class Epi>
; __device__ __forceinline__ void gemm_tile_wf32(const u16* __restrict__ A, long lda, const int* arow, WM wmap, long kstride, int K,
;                                                u16* smem, Epi epi) {
;     ...
;     if (kt + 2 < nk) { asm volatile("s_waitcnt vmcnt(8)" ::: "memory"); } else { asm volatile("s_waitcnt vmcnt(0)" ::: "memory"); }
;     __syncthreads();
;     if (kt + 2 < nk) { STAGE_A((kt + 2) << 6, 0); }
.LBB0_898:
	s_andn2_b64 vcc, exec, s[36:37]
	s_waitcnt lgkmcnt(0)
	s_barrier
	s_cbranch_vccnz .LBB0_900
	v_readfirstlane_b32 s36, v186
	v_lshl_add_u64 v[156:157], v[156:157], 0, s[24:25]
	s_mov_b32 m0, s36
	v_readfirstlane_b32 s36, v200
	v_lshl_add_u64 v[158:159], v[158:159], 0, s[24:25]
	global_load_lds_dwordx4 v[156:157], off
	s_mov_b32 m0, s36
	v_readfirstlane_b32 s36, v201
	v_lshl_add_u64 v[160:161], v[160:161], 0, s[24:25]
	global_load_lds_dwordx4 v[158:159], off
	s_mov_b32 m0, s36
	v_readfirstlane_b32 s36, v202
	v_lshl_add_u64 v[162:163], v[162:163], 0, s[24:25]
	global_load_lds_dwordx4 v[160:161], off
	s_mov_b32 m0, s36
	s_nop 0
	global_load_lds_dwordx4 v[162:163], off

; template <class WM, class Epi>
; __device__ __forceinline__ void gemm_tile_wf32(const u16* __restrict__ A, long lda, const int* arow, WM wmap, long kstride, int K,
;                                                u16* smem, Epi epi) {
;     ...
;     COMPUTE(0);
;     WRITE_W(wr1, 1);
;     if (kt + 2 < nk) { asm volatile("s_waitcnt vmcnt(8)" ::: "memory"); } else { asm volatile("s_waitcnt vmcnt(0)" ::: "memory"); }
.Lmoe0_w4:
	s_waitcnt vmcnt(4)
	s_branch .Lmoe0_wd

; #define LOAD_W(R, k0)                                                           \
;   {                                                                             \
;     _Pragma("unroll") for (int i = 0; i < 8; i++) R[i] = *(const f32x4*)(wp0 + (long)((k0) + 8 * i) * kstride); \
;   }
; template <class WM, class Epi>
; __device__ __forceinline__ void gemm_tile_wf32(const u16* __restrict__ A, long lda, const int* arow, WM wmap, long kstride, int K,
;                                                u16* smem, Epi epi) {
;     ...
;     asm volatile("s_waitcnt vmcnt(8)" ::: "memory");
;     __syncthreads();
;     STAGE_A((kt + 1) << 6, 1);
;     if (kt + 2 < nk) LOAD_W(wr0, (kt + 2) << 6);
;     COMPUTE(0);
;     WRITE_W(wr1, 1);
;     if (kt + 2 < nk) { asm volatile("s_waitcnt vmcnt(8)" ::: "memory"); } else { asm volatile("s_waitcnt vmcnt(0)" ::: "memory"); }
;     __syncthreads();
;     if (kt + 2 < nk) { STAGE_A((kt + 2) << 6, 0); }
;     if (kt + 3 < nk) LOAD_W(wr1, (kt + 3) << 6);
;     COMPUTE(1);
;     if (kt + 2 < nk) WRITE_W(wr0, 0);
.LBB0_982:
	s_waitcnt vmcnt(8)
	v_cvt_pk_bf16_f32 v150, v0, v1
	v_cvt_pk_bf16_f32 v151, v2, v3
	ds_write_b64 v162, v[150:151] offset:16384
	v_cvt_pk_bf16_f32 v150, v4, v5
	v_cvt_pk_bf16_f32 v151, v6, v7
	ds_write_b64 v163, v[150:151] offset:16384
	v_cvt_pk_bf16_f32 v150, v8, v9
	v_cvt_pk_bf16_f32 v151, v10, v11
	ds_write_b64 v162, v[150:151] offset:20480
	v_cvt_pk_bf16_f32 v150, v12, v13
	v_cvt_pk_bf16_f32 v151, v14, v15
	ds_write_b64 v163, v[150:151] offset:20480
	v_cvt_pk_bf16_f32 v150, v24, v25
	v_cvt_pk_bf16_f32 v151, v26, v27
	ds_write_b64 v162, v[150:151] offset:24576
	v_cvt_pk_bf16_f32 v150, v28, v29
	v_cvt_pk_bf16_f32 v151, v30, v31
	ds_write_b64 v163, v[150:151] offset:24576
	v_cvt_pk_bf16_f32 v150, v40, v41
	v_cvt_pk_bf16_f32 v151, v42, v43
	ds_write_b64 v162, v[150:151] offset:28672
	v_cvt_pk_bf16_f32 v150, v44, v45
	v_cvt_pk_bf16_f32 v151, v46, v47
	v_add_u32_e32 v154, 0x8000, v161
	ds_write_b64 v163, v[150:151] offset:28672
	v_lshl_add_u64 v[150:151], s[34:35], 0, v[140:141]
	v_readfirstlane_b32 s36, v154
	v_lshl_add_u64 v[152:153], v[150:151], 0, s[24:25]
	s_mov_b32 m0, s36
	v_add_u32_e32 v156, 0x9000, v161
	s_waitcnt vmcnt(8)
	s_waitcnt lgkmcnt(0)
	s_barrier
	global_load_lds_dwordx4 v[152:153], off
	v_lshl_add_u64 v[152:153], s[34:35], 0, v[142:143]
	v_readfirstlane_b32 s36, v156
	v_lshl_add_u64 v[154:155], v[152:153], 0, s[24:25]
	s_mov_b32 m0, s36
	v_add_u32_e32 v172, 0xa000, v161
	global_load_lds_dwordx4 v[154:155], off
	v_lshl_add_u64 v[154:155], s[34:35], 0, v[144:145]
	v_readfirstlane_b32 s36, v172
	v_lshl_add_u64 v[156:157], v[154:155], 0, s[24:25]
	s_mov_b32 m0, s36
	v_add_u32_e32 v172, 0xb000, v161
	global_load_lds_dwordx4 v[156:157], off
	v_lshl_add_u64 v[156:157], s[34:35], 0, v[146:147]
	v_readfirstlane_b32 s36, v172
	v_lshl_add_u64 v[180:181], v[156:157], 0, s[24:25]
	s_mov_b32 m0, s36
	s_cmp_lt_u32 s23, 6
	global_load_lds_dwordx4 v[180:181], off
	s_cselect_b64 s[38:39], -1, 0
	s_cmp_gt_u32 s23, 5
	s_cselect_b64 s[36:37], -1, 0
	s_and_b64 vcc, exec, s[36:37]
	s_cbranch_vccnz .LBB0_984
	v_add_co_u32_e32 v0, vcc, 0xfff10000, v148
	s_nop 1
	v_addc_co_u32_e32 v1, vcc, -1, v149, vcc
	v_add_co_u32_e32 v4, vcc, 0xfff20000, v148
	s_nop 1
	v_addc_co_u32_e32 v5, vcc, -1, v149, vcc
	v_add_co_u32_e32 v8, vcc, 0xfff30000, v148
	global_load_dwordx4 v[0:3], v[0:1], off
	s_nop 0
	global_load_dwordx4 v[4:7], v[4:5], off
	v_addc_co_u32_e32 v9, vcc, -1, v149, vcc
	v_add_co_u32_e32 v12, vcc, 0xfff40000, v148
	s_nop 1
	v_addc_co_u32_e32 v13, vcc, -1, v149, vcc
	v_add_co_u32_e32 v24, vcc, 0xfff50000, v148
	global_load_dwordx4 v[8:11], v[8:9], off
	s_nop 0
	global_load_dwordx4 v[12:15], v[12:13], off
	v_addc_co_u32_e32 v25, vcc, -1, v149, vcc
	v_add_co_u32_e32 v28, vcc, 0xfff60000, v148
	s_nop 1
	v_addc_co_u32_e32 v29, vcc, -1, v149, vcc
	v_add_co_u32_e32 v40, vcc, 0xfff70000, v148
	global_load_dwordx4 v[24:27], v[24:25], off
	s_nop 0
	global_load_dwordx4 v[28:31], v[28:29], off
	v_addc_co_u32_e32 v41, vcc, -1, v149, vcc
	v_add_co_u32_e32 v44, vcc, 0xfff80000, v148
	s_nop 1
	v_addc_co_u32_e32 v45, vcc, -1, v149, vcc
	global_load_dwordx4 v[40:43], v[40:41], off
	s_nop 0
	global_load_dwordx4 v[44:47], v[44:45], off
; template <class WM, class Epi>
; __device__ __forceinline__ void gemm_tile_wf32(const u16* __restrict__ A, long lda, const int* arow, WM wmap, long kstride, int K,
;                                                u16* smem, Epi epi) {
;     ...
;     COMPUTE(0);
;     WRITE_W(wr1, 1);
.LBB0_984:
	ds_read_b64_tr_b16 v[180:181], v165 offset:16384
	ds_read_b64_tr_b16 v[182:183], v166 offset:17408
	ds_read_b128 v[184:187], v164
	ds_read_b128 v[188:191], v164 offset:2048
	ds_read_b64_tr_b16 v[194:195], v166 offset:25600
	ds_read_b64_tr_b16 v[192:193], v165 offset:24576
	ds_read_b64_tr_b16 v[196:197], v167 offset:16384
	ds_read_b64_tr_b16 v[198:199], v168 offset:17408
	ds_read_b64_tr_b16 v[202:203], v168 offset:25600
	ds_read_b64_tr_b16 v[200:201], v167 offset:24576
	ds_read_b64_tr_b16 v[204:205], v169 offset:16384
	ds_read_b64_tr_b16 v[206:207], v170 offset:17408
	ds_read_b64_tr_b16 v[210:211], v170 offset:25600
	ds_read_b64_tr_b16 v[208:209], v169 offset:24576
	ds_read_b64_tr_b16 v[212:213], v171 offset:16384
	ds_read_b64_tr_b16 v[214:215], v173 offset:17408
	ds_read_b64_tr_b16 v[218:219], v173 offset:25600
	ds_read_b64_tr_b16 v[216:217], v171 offset:24576
	s_waitcnt lgkmcnt(0)
	v_mfma_f32_16x16x32_bf16 v[124:127], v[180:183], v[184:187], v[124:127]
	s_mov_b64 s[40:41], -1
	s_and_b64 vcc, exec, s[36:37]
	v_mfma_f32_16x16x32_bf16 v[120:123], v[196:199], v[184:187], v[120:123]
	v_mfma_f32_16x16x32_bf16 v[116:119], v[204:207], v[184:187], v[116:119]
	v_mfma_f32_16x16x32_bf16 v[112:115], v[212:215], v[184:187], v[112:115]
	v_mfma_f32_16x16x32_bf16 v[108:111], v[180:183], v[188:191], v[108:111]
	v_mfma_f32_16x16x32_bf16 v[184:187], v[196:199], v[188:191], v[104:107]
	v_mfma_f32_16x16x32_bf16 v[100:103], v[204:207], v[188:191], v[100:103]
	v_mfma_f32_16x16x32_bf16 v[96:99], v[212:215], v[188:191], v[96:99]
	s_nop 0
	ds_read_b128 v[104:107], v164 offset:4096
	ds_read_b128 v[188:191], v164 offset:6144
	s_waitcnt lgkmcnt(0)
	v_mfma_f32_16x16x32_bf16 v[224:227], v[196:199], v[104:107], v[88:91]
	s_cbranch_vccnz .Lmoe1_w4
	s_waitcnt vmcnt(12)
.Lmoe1_wd:
	s_nop 2
	v_cvt_pk_bf16_f32 v88, v16, v17
	v_mfma_f32_16x16x32_bf16 v[228:231], v[204:207], v[104:107], v[84:87]
	v_cvt_pk_bf16_f32 v89, v18, v19
	v_mfma_f32_16x16x32_bf16 v[196:199], v[196:199], v[188:191], v[64:67]
	s_nop 2
	ds_read_b128 v[64:67], v174
	ds_read_b128 v[84:87], v174 offset:2048
	v_mfma_f32_16x16x32_bf16 v[220:223], v[180:183], v[104:107], v[92:95]
	v_mfma_f32_16x16x32_bf16 v[232:235], v[212:215], v[104:107], v[80:83]
	v_mfma_f32_16x16x32_bf16 v[180:183], v[180:183], v[188:191], v[68:71]
	s_waitcnt lgkmcnt(0)
	v_mfma_f32_16x16x32_bf16 v[104:107], v[192:195], v[64:67], v[124:127]
	v_mfma_f32_16x16x32_bf16 v[68:71], v[192:195], v[84:87], v[108:111]
	s_nop 2
	ds_read_b128 v[108:111], v174 offset:4096
	ds_read_b128 v[124:127], v174 offset:6144
	ds_write_b64 v162, v[88:89] offset:49152
	v_mfma_f32_16x16x32_bf16 v[204:207], v[204:207], v[188:191], v[76:79]
	v_mfma_f32_16x16x32_bf16 v[188:191], v[212:215], v[188:191], v[72:75]
	v_mfma_f32_16x16x32_bf16 v[92:95], v[200:203], v[64:67], v[120:123]
	v_mfma_f32_16x16x32_bf16 v[80:83], v[208:211], v[64:67], v[116:119]
	s_nop 1
	v_cvt_pk_bf16_f32 v120, v56, v57
	v_cvt_pk_bf16_f32 v121, v58, v59
	v_mfma_f32_16x16x32_bf16 v[64:67], v[216:219], v[64:67], v[112:115]
	v_cvt_pk_bf16_f32 v116, v52, v53
	v_cvt_pk_bf16_f32 v117, v54, v55
	v_mfma_f32_16x16x32_bf16 v[72:75], v[200:203], v[84:87], v[184:187]
	v_cvt_pk_bf16_f32 v112, v36, v37
	v_cvt_pk_bf16_f32 v113, v38, v39
	v_mfma_f32_16x16x32_bf16 v[76:79], v[208:211], v[84:87], v[100:103]
	v_mfma_f32_16x16x32_bf16 v[84:87], v[216:219], v[84:87], v[96:99]
	s_nop 1
	v_cvt_pk_bf16_f32 v100, v32, v33
	v_cvt_pk_bf16_f32 v101, v34, v35
	v_cvt_pk_bf16_f32 v96, v20, v21
	v_cvt_pk_bf16_f32 v97, v22, v23
	ds_write_b64 v163, v[96:97] offset:49152
	ds_write_b64 v162, v[100:101] offset:53248
	ds_write_b64 v163, v[112:113] offset:53248
	v_cvt_pk_bf16_f32 v112, v48, v49
	v_cvt_pk_bf16_f32 v113, v50, v51
	s_waitcnt lgkmcnt(0)
	v_mfma_f32_16x16x32_bf16 v[88:91], v[192:195], v[108:111], v[220:223]
	ds_write_b64 v162, v[112:113] offset:57344
	ds_write_b64 v163, v[116:117] offset:57344
	ds_write_b64 v162, v[120:121] offset:61440
	v_mfma_f32_16x16x32_bf16 v[96:99], v[200:203], v[108:111], v[224:227]
	v_mfma_f32_16x16x32_bf16 v[100:103], v[208:211], v[108:111], v[228:231]
	v_mfma_f32_16x16x32_bf16 v[108:111], v[216:219], v[108:111], v[232:235]
	v_mfma_f32_16x16x32_bf16 v[112:115], v[192:195], v[124:127], v[180:183]
	v_mfma_f32_16x16x32_bf16 v[116:119], v[200:203], v[124:127], v[196:199]
	s_nop 1
	v_cvt_pk_bf16_f32 v180, v60, v61
	v_cvt_pk_bf16_f32 v181, v62, v63
	ds_write_b64 v163, v[180:181] offset:61440
	v_mfma_f32_16x16x32_bf16 v[120:123], v[208:211], v[124:127], v[204:207]
	v_mfma_f32_16x16x32_bf16 v[124:127], v[216:219], v[124:127], v[188:191]
	s_cbranch_vccz .LBB0_986
	s_waitcnt vmcnt(0)
	s_mov_b64 s[40:41], 0

; template <class WM, class Epi>
; __device__ __forceinline__ void gemm_tile_wf32(const u16* __restrict__ A, long lda, const int* arow, WM wmap, long kstride, int K,
;                                                u16* smem, Epi epi) {
;     ...
;     if (kt + 2 < nk) { asm volatile("s_waitcnt vmcnt(8)" ::: "memory"); } else { asm volatile("s_waitcnt vmcnt(0)" ::: "memory"); }
;     __syncthreads();
;     if (kt + 2 < nk) { STAGE_A((kt + 2) << 6, 0); }
.LBB0_988:
	s_andn2_b64 vcc, exec, s[38:39]
	s_waitcnt lgkmcnt(0)
	s_barrier
	s_cbranch_vccnz .LBB0_990
	v_readfirstlane_b32 s38, v161
	v_lshl_add_u64 v[150:151], v[150:151], 0, s[26:27]
	s_mov_b32 m0, s38
	v_readfirstlane_b32 s38, v175
	v_lshl_add_u64 v[152:153], v[152:153], 0, s[26:27]
	global_load_lds_dwordx4 v[150:151], off
	s_mov_b32 m0, s38
	v_readfirstlane_b32 s38, v176
	v_lshl_add_u64 v[154:155], v[154:155], 0, s[26:27]
	global_load_lds_dwordx4 v[152:153], off
	s_mov_b32 m0, s38
	v_readfirstlane_b32 s38, v178
	v_lshl_add_u64 v[156:157], v[156:157], 0, s[26:27]
	global_load_lds_dwordx4 v[154:155], off
	s_mov_b32 m0, s38
	s_nop 0
	global_load_lds_dwordx4 v[156:157], off
